# s_sleep 3 (instead of 2) in FFN-in GEMM load segments
# speedup vs baseline: 1.0044x; 1.0044x over previous
; template <class Epi, class Sched, bool ALIGN_EPI = false, bool SP2 = false>
; __device__ __forceinline__ void gemm_phase(PG8_LAS unsigned char* lds, const Gemm g, const Sched& S, const Epi& E) {
;     ...
;         const bool has_next = S.next(ui + 1, nxt);
;         const char* nA = has_next ? (const char*)g.A + (size_t)nxt.pm * tstepA : cA; const char* nB = has_next ? (const char*)g.Bt + (size_t)nxt.pn * tstepB : cB;
.LBB0_477:
	s_ashr_i32 s27, s26, 31
	s_lshl_b64 s[2:3], s[26:27], 15
	v_readlane_b32 s10, v255, 15
	s_add_u32 s28, s10, s2
	v_readlane_b32 s2, v255, 16
	s_addc_u32 s29, s2, s3
	s_ashr_i32 s25, s24, 31
	s_lshl_b64 s[2:3], s[24:25], 19
	s_add_u32 s30, s19, s2
	s_addc_u32 s31, s22, s3
	s_add_u32 s44, s34, 0x800000
	s_addc_u32 s45, s35, 0
	s_add_u32 s42, s34, 0xc00000
	s_addc_u32 s43, s35, 0
	s_add_i32 s61, 0, 0x10000
	s_and_b64 s[2:3], s[40:41], exec
	s_cselect_b32 s25, s29, s35
	s_cselect_b32 s27, s28, s34
	s_add_i32 s97, 0, 0x14000
	v_add_u32_e32 v142, s61, v97
	v_add_u32_e32 v143, s97, v97
	ds_read_b128 v[0:3], v142
	ds_read_b128 v[4:7], v142 offset:1024
	ds_read_b128 v[8:11], v142 offset:2048
	ds_read_b128 v[12:15], v142 offset:3072
	ds_read_b128 v[16:19], v143
	s_waitcnt lgkmcnt(0)
	ds_read_b128 v[20:23], v143 offset:1024
	ds_read_b128 v[24:27], v143 offset:2048
	ds_read_b128 v[28:31], v143 offset:3072
	s_and_b64 s[2:3], s[40:41], exec
	s_cselect_b32 s57, s31, s1
	s_cselect_b32 s58, s30, s0
	s_add_u32 s2, s34, 0x404000
	s_addc_u32 s3, s35, 0
	s_add_i32 s59, s23, 0xc000
	v_lshl_add_u64 v[64:65], s[2:3], 0, v[130:131]
	s_mov_b32 m0, s59
	s_add_i32 s60, s23, 0xe000
	ds_read_b128 v[32:35], v156
	ds_read_b128 v[36:39], v156 offset:1024
	ds_read_b128 v[40:43], v156 offset:2048
	ds_read_b128 v[44:47], v156 offset:3072
	ds_read_b128 v[48:51], v156 offset:4096
	ds_read_b128 v[52:55], v156 offset:5120
	ds_read_b128 v[56:59], v156 offset:6144
	ds_read_b128 v[60:63], v156 offset:7168
	global_load_lds_dwordx4 v[64:65], off
	v_lshl_add_u64 v[64:65], s[2:3], 0, v[134:135]
	s_mov_b32 m0, s60
	s_nop 0
	global_load_lds_dwordx4 v[64:65], off
	s_sleep 3
	s_waitcnt vmcnt(8)
	s_waitcnt lgkmcnt(0)
	s_barrier
	s_setprio 1
	s_waitcnt lgkmcnt(0)
	v_mfma_f32_16x16x32_bf16 v[88:91], v[0:3], v[56:59], 0
	v_mfma_f32_16x16x32_bf16 v[64:67], v[0:3], v[32:35], 0
	v_mfma_f32_16x16x32_bf16 v[68:71], v[8:11], v[32:35], 0
	v_mfma_f32_16x16x32_bf16 v[72:75], v[0:3], v[40:43], 0
	v_mfma_f32_16x16x32_bf16 v[76:79], v[8:11], v[40:43], 0
	v_mfma_f32_16x16x32_bf16 v[80:83], v[0:3], v[48:51], 0
	v_mfma_f32_16x16x32_bf16 v[84:87], v[8:11], v[48:51], 0
	v_mfma_f32_16x16x32_bf16 v[92:95], v[4:7], v[60:63], v[88:91]
	v_mfma_f32_16x16x32_bf16 v[88:91], v[8:11], v[56:59], 0
	v_mfma_f32_16x16x32_bf16 v[64:67], v[4:7], v[36:39], v[64:67]
	v_mfma_f32_16x16x32_bf16 v[68:71], v[12:15], v[36:39], v[68:71]
	v_mfma_f32_16x16x32_bf16 v[72:75], v[4:7], v[44:47], v[72:75]
	v_mfma_f32_16x16x32_bf16 v[76:79], v[12:15], v[44:47], v[76:79]
	v_mfma_f32_16x16x32_bf16 v[80:83], v[4:7], v[52:55], v[80:83]
	v_mfma_f32_16x16x32_bf16 v[84:87], v[12:15], v[52:55], v[84:87]
	v_mfma_f32_16x16x32_bf16 v[102:105], v[12:15], v[60:63], v[88:91]
	s_setprio 0
	s_setprio 1
	v_mfma_f32_16x16x32_bf16 v[88:91], v[16:19], v[32:35], 0
	v_mfma_f32_16x16x32_bf16 v[32:35], v[24:27], v[32:35], 0
	v_mfma_f32_16x16x32_bf16 v[110:113], v[20:23], v[36:39], v[88:91]
	v_mfma_f32_16x16x32_bf16 v[32:35], v[28:31], v[36:39], v[32:35]
	v_mfma_f32_16x16x32_bf16 v[36:39], v[16:19], v[40:43], 0
	v_mfma_f32_16x16x32_bf16 v[40:43], v[24:27], v[40:43], 0
	v_mfma_f32_16x16x32_bf16 v[36:39], v[20:23], v[44:47], v[36:39]
	v_mfma_f32_16x16x32_bf16 v[40:43], v[28:31], v[44:47], v[40:43]
	v_mfma_f32_16x16x32_bf16 v[44:47], v[16:19], v[48:51], 0
	v_mfma_f32_16x16x32_bf16 v[48:51], v[24:27], v[48:51], 0
	v_mfma_f32_16x16x32_bf16 v[44:47], v[20:23], v[52:55], v[44:47]
	v_mfma_f32_16x16x32_bf16 v[48:51], v[28:31], v[52:55], v[48:51]
	v_mfma_f32_16x16x32_bf16 v[52:55], v[16:19], v[56:59], 0
	v_mfma_f32_16x16x32_bf16 v[56:59], v[24:27], v[56:59], 0
	v_mfma_f32_16x16x32_bf16 v[52:55], v[20:23], v[60:63], v[52:55]
	v_mfma_f32_16x16x32_bf16 v[56:59], v[28:31], v[60:63], v[56:59]
	s_setprio 0
	s_barrier
	v_lshl_add_u64 v[154:155], s[0:1], 0, v[132:133]
	s_mov_b64 s[2:3], 0x100
	s_add_i32 s61, s61, s9
	v_lshl_add_u64 v[144:145], v[154:155], 0, s[2:3]
	s_mov_b32 m0, s61
	v_lshl_add_u64 v[178:179], s[0:1], 0, v[136:137]
	s_add_i32 s96, s61, 0x2000
	ds_read_b128 v[60:63], v156 offset:16384
	ds_read_b128 v[88:91], v156 offset:17408
	ds_read_b128 v[98:101], v156 offset:18432
	ds_read_b128 v[106:109], v156 offset:19456
	ds_read_b128 v[114:117], v156 offset:20480
	ds_read_b128 v[118:121], v156 offset:21504
	ds_read_b128 v[122:125], v156 offset:22528
	ds_read_b128 v[126:129], v156 offset:23552
	global_load_lds_dwordx4 v[144:145], off
	v_lshl_add_u64 v[144:145], v[178:179], 0, s[2:3]
	s_add_u32 s2, s0, 0x40100
	s_mov_b32 m0, s96
	s_addc_u32 s3, s1, 0
	s_add_i32 s97, s97, s9
	global_load_lds_dwordx4 v[144:145], off
	v_lshl_add_u64 v[144:145], s[2:3], 0, v[132:133]
	s_mov_b32 m0, s97
	s_add_i32 s98, s97, 0x2000
	global_load_lds_dwordx4 v[144:145], off
	v_lshl_add_u64 v[144:145], s[2:3], 0, v[136:137]
	s_mov_b32 m0, s98
	s_nop 0
	global_load_lds_dwordx4 v[144:145], off
	v_lshl_add_u64 v[144:145], s[44:45], 0, v[130:131]
	s_mov_b32 m0, s23
	s_nop 0
	global_load_lds_dwordx4 v[144:145], off
	v_lshl_add_u64 v[144:145], s[44:45], 0, v[134:135]
	s_mov_b32 m0, s39
	s_nop 0
	global_load_lds_dwordx4 v[144:145], off
	s_sleep 3
	s_waitcnt vmcnt(8)
	s_waitcnt lgkmcnt(0)
	s_barrier
	s_setprio 1
	s_waitcnt lgkmcnt(0)
	v_mfma_f32_16x16x32_bf16 v[144:147], v[0:3], v[60:63], 0
	v_mfma_f32_16x16x32_bf16 v[158:161], v[0:3], v[98:101], 0
	v_mfma_f32_16x16x32_bf16 v[166:169], v[0:3], v[114:117], 0
	v_mfma_f32_16x16x32_bf16 v[0:3], v[0:3], v[122:125], 0
	v_mfma_f32_16x16x32_bf16 v[146:149], v[4:7], v[88:91], v[144:147]
	v_mfma_f32_16x16x32_bf16 v[158:161], v[4:7], v[106:109], v[158:161]
	v_mfma_f32_16x16x32_bf16 v[166:169], v[4:7], v[118:121], v[166:169]
	v_mfma_f32_16x16x32_bf16 v[0:3], v[4:7], v[126:129], v[0:3]
	v_mfma_f32_16x16x32_bf16 v[4:7], v[8:11], v[122:125], 0
	v_mfma_f32_16x16x32_bf16 v[150:153], v[8:11], v[60:63], 0
	v_mfma_f32_16x16x32_bf16 v[162:165], v[8:11], v[98:101], 0
	v_mfma_f32_16x16x32_bf16 v[170:173], v[8:11], v[114:117], 0
	v_mfma_f32_16x16x32_bf16 v[4:7], v[12:15], v[126:129], v[4:7]
	v_mfma_f32_16x16x32_bf16 v[150:153], v[12:15], v[88:91], v[150:153]
	v_mfma_f32_16x16x32_bf16 v[162:165], v[12:15], v[106:109], v[162:165]
	v_mfma_f32_16x16x32_bf16 v[170:173], v[12:15], v[118:121], v[170:173]
	s_setprio 0
	s_setprio 1
	v_mfma_f32_16x16x32_bf16 v[8:11], v[16:19], v[60:63], 0
	v_mfma_f32_16x16x32_bf16 v[12:15], v[20:23], v[88:91], v[8:11]
	v_mfma_f32_16x16x32_bf16 v[8:11], v[24:27], v[60:63], 0
	v_mfma_f32_16x16x32_bf16 v[174:177], v[28:31], v[88:91], v[8:11]
	v_mfma_f32_16x16x32_bf16 v[8:11], v[16:19], v[98:101], 0
	v_mfma_f32_16x16x32_bf16 v[188:191], v[20:23], v[106:109], v[8:11]
	v_mfma_f32_16x16x32_bf16 v[8:11], v[24:27], v[98:101], 0
	v_mfma_f32_16x16x32_bf16 v[192:195], v[28:31], v[106:109], v[8:11]
	v_mfma_f32_16x16x32_bf16 v[8:11], v[16:19], v[114:117], 0
	v_mfma_f32_16x16x32_bf16 v[196:199], v[20:23], v[118:121], v[8:11]
	v_mfma_f32_16x16x32_bf16 v[8:11], v[24:27], v[114:117], 0
	v_mfma_f32_16x16x32_bf16 v[200:203], v[28:31], v[118:121], v[8:11]
	v_mfma_f32_16x16x32_bf16 v[8:11], v[16:19], v[122:125], 0
	v_mfma_f32_16x16x32_bf16 v[204:207], v[20:23], v[126:129], v[8:11]
	v_mfma_f32_16x16x32_bf16 v[8:11], v[24:27], v[122:125], 0
	v_mfma_f32_16x16x32_bf16 v[208:211], v[28:31], v[126:129], v[8:11]
	s_setprio 0
	s_barrier
	s_add_i32 s99, 0, 0x18000
	s_add_i32 vcc_hi, 0, 0x1c000
	v_add_u32_e32 v144, s99, v97
	v_add_u32_e32 v145, vcc_hi, v97
	s_nop 0
	ds_read_b128 v[8:11], v144
	ds_read_b128 v[20:23], v144 offset:1024
	ds_read_b128 v[28:31], v144 offset:2048
	ds_read_b128 v[212:215], v144 offset:3072
	ds_read_b128 v[216:219], v145
	ds_read_b128 v[220:223], v145 offset:1024
	ds_read_b128 v[234:237], v145 offset:2048
	ds_read_b128 v[238:241], v145 offset:3072
	s_add_u32 s2, s34, 0x804000
	s_addc_u32 s3, s35, 0
	s_mov_b32 m0, s46
	v_lshl_add_u64 v[60:61], s[2:3], 0, v[130:131]
	ds_read_b128 v[16:19], v156 offset:32768
	ds_read_b128 v[24:27], v156 offset:33792
	ds_read_b128 v[242:245], v156 offset:34816
	ds_read_b128 v[246:249], v156 offset:35840
	ds_read_b128 v[228:231], v156 offset:36864
	ds_read_b128 v[180:183], v156 offset:37888
	ds_read_b128 v[184:187], v156 offset:38912
	ds_read_b128 v[224:227], v156 offset:39936
	global_load_lds_dwordx4 v[60:61], off
	v_lshl_add_u64 v[60:61], s[2:3], 0, v[134:135]
	s_mov_b32 m0, s47
	s_nop 0
	global_load_lds_dwordx4 v[60:61], off
	s_sleep 3
	s_waitcnt vmcnt(8)
	s_waitcnt lgkmcnt(0)
	s_barrier
	s_setprio 1
	s_waitcnt lgkmcnt(0)
	v_mfma_f32_16x16x32_bf16 v[60:63], v[8:11], v[16:19], v[64:67]
	v_mfma_f32_16x16x32_bf16 v[122:125], v[20:23], v[24:27], v[60:63]
	v_mfma_f32_16x16x32_bf16 v[60:63], v[28:31], v[16:19], v[68:71]
	v_mfma_f32_16x16x32_bf16 v[114:117], v[212:215], v[24:27], v[60:63]
	v_mfma_f32_16x16x32_bf16 v[60:63], v[8:11], v[242:245], v[72:75]
	v_mfma_f32_16x16x32_bf16 v[106:109], v[20:23], v[246:249], v[60:63]
	v_mfma_f32_16x16x32_bf16 v[60:63], v[28:31], v[242:245], v[76:79]
	v_mfma_f32_16x16x32_bf16 v[98:101], v[212:215], v[246:249], v[60:63]
	v_mfma_f32_16x16x32_bf16 v[60:63], v[8:11], v[228:231], v[80:83]
	v_mfma_f32_16x16x32_bf16 v[88:91], v[20:23], v[180:183], v[60:63]
	v_mfma_f32_16x16x32_bf16 v[60:63], v[28:31], v[228:231], v[84:87]
	v_mfma_f32_16x16x32_bf16 v[80:83], v[212:215], v[180:183], v[60:63]
	v_mfma_f32_16x16x32_bf16 v[60:63], v[8:11], v[184:187], v[92:95]
	v_mfma_f32_16x16x32_bf16 v[72:75], v[20:23], v[224:227], v[60:63]
	v_mfma_f32_16x16x32_bf16 v[60:63], v[28:31], v[184:187], v[102:105]
	v_mfma_f32_16x16x32_bf16 v[60:63], v[212:215], v[224:227], v[60:63]
	s_setprio 0
	s_setprio 1
	v_mfma_f32_16x16x32_bf16 v[64:67], v[216:219], v[16:19], v[110:113]
	v_mfma_f32_16x16x32_bf16 v[16:19], v[234:237], v[16:19], v[32:35]
	v_mfma_f32_16x16x32_bf16 v[118:121], v[238:241], v[24:27], v[16:19]
	v_mfma_f32_16x16x32_bf16 v[16:19], v[216:219], v[242:245], v[36:39]
	v_mfma_f32_16x16x32_bf16 v[110:113], v[220:223], v[246:249], v[16:19]
	v_mfma_f32_16x16x32_bf16 v[16:19], v[234:237], v[242:245], v[40:43]
	v_mfma_f32_16x16x32_bf16 v[102:105], v[238:241], v[246:249], v[16:19]
	v_mfma_f32_16x16x32_bf16 v[16:19], v[216:219], v[228:231], v[44:47]
	v_mfma_f32_16x16x32_bf16 v[92:95], v[220:223], v[180:183], v[16:19]
	v_mfma_f32_16x16x32_bf16 v[16:19], v[234:237], v[228:231], v[48:51]
	v_mfma_f32_16x16x32_bf16 v[84:87], v[238:241], v[180:183], v[16:19]
	v_mfma_f32_16x16x32_bf16 v[16:19], v[216:219], v[184:187], v[52:55]
	v_mfma_f32_16x16x32_bf16 v[76:79], v[220:223], v[224:227], v[16:19]
	v_mfma_f32_16x16x32_bf16 v[16:19], v[234:237], v[184:187], v[56:59]
	v_mfma_f32_16x16x32_bf16 v[126:129], v[220:223], v[24:27], v[64:67]
	v_mfma_f32_16x16x32_bf16 v[68:71], v[238:241], v[224:227], v[16:19]
	s_setprio 0
	s_barrier
; template <class Epi, class Sched, bool ALIGN_EPI = false, bool SP2 = false>
; __device__ __forceinline__ void gemm_phase(PG8_LAS unsigned char* lds, const Gemm g, const Sched& S, const Epi& E) {
;     ...
;         for (int t = (Epi::PEEL ? 2 : 0); t < nt; t += 2) {
;             const bool last = (t == nt - 2);
;             const char* a1 = cA + (size_t)(t + 1) * kstepA;
;             const char* a2 = last ? nA : cA + (size_t)(t + 2) * kstepA; const char* b2 = last ? nB : cB + (size_t)(t + 2) * kstepB;
;             const char* a3 = a2 + kstepA; const char* b3 = b2 + kstepB;
	s_mov_b64 s[2:3], 0x180
	s_add_i32 s99, s99, s9
	s_nop 1
	v_lshl_add_u64 v[16:17], v[154:155], 0, s[2:3]
	s_mov_b32 m0, s99
	s_add_i32 vcc_lo, s99, 0x2000
	ds_read_b128 v[36:39], v156 offset:49152
	ds_read_b128 v[44:47], v156 offset:50176
	ds_read_b128 v[180:183], v156 offset:51200
	ds_read_b128 v[184:187], v156 offset:52224
	ds_read_b128 v[224:227], v156 offset:53248
	ds_read_b128 v[228:231], v156 offset:54272
	ds_read_b128 v[242:245], v156 offset:55296
	ds_read_b128 v[246:249], v156 offset:56320
	global_load_lds_dwordx4 v[16:17], off
	v_lshl_add_u64 v[16:17], v[178:179], 0, s[2:3]
	s_add_u32 s2, s0, 0x40180
	s_mov_b32 m0, vcc_lo
	s_addc_u32 s3, s1, 0
	s_add_i32 vcc_hi, vcc_hi, s9
	global_load_lds_dwordx4 v[16:17], off
	v_lshl_add_u64 v[16:17], s[2:3], 0, v[132:133]
	s_mov_b32 m0, vcc_hi
	s_add_i32 s38, vcc_hi, 0x2000
	global_load_lds_dwordx4 v[16:17], off
	v_lshl_add_u64 v[16:17], s[2:3], 0, v[136:137]
	s_mov_b32 m0, s38
	s_nop 0
	global_load_lds_dwordx4 v[16:17], off
	v_lshl_add_u64 v[16:17], s[42:43], 0, v[130:131]
	s_mov_b32 m0, s49
	s_nop 0
	global_load_lds_dwordx4 v[16:17], off
	v_lshl_add_u64 v[16:17], s[42:43], 0, v[134:135]
	s_mov_b32 m0, s50
	s_nop 0
	global_load_lds_dwordx4 v[16:17], off
	s_sleep 3
	s_waitcnt vmcnt(8)
	s_waitcnt lgkmcnt(0)
	s_barrier
	s_setprio 1
	s_waitcnt lgkmcnt(0)
	v_mfma_f32_16x16x32_bf16 v[16:19], v[8:11], v[36:39], v[146:149]
	v_mfma_f32_16x16x32_bf16 v[56:59], v[20:23], v[44:47], v[16:19]
	v_mfma_f32_16x16x32_bf16 v[16:19], v[28:31], v[36:39], v[150:153]
	v_mfma_f32_16x16x32_bf16 v[48:51], v[212:215], v[44:47], v[16:19]
	v_mfma_f32_16x16x32_bf16 v[16:19], v[8:11], v[180:183], v[158:161]
	v_mfma_f32_16x16x32_bf16 v[40:43], v[20:23], v[184:187], v[16:19]
	v_mfma_f32_16x16x32_bf16 v[16:19], v[28:31], v[180:183], v[162:165]
	v_mfma_f32_16x16x32_bf16 v[32:35], v[212:215], v[184:187], v[16:19]
	v_mfma_f32_16x16x32_bf16 v[16:19], v[8:11], v[224:227], v[166:169]
	v_mfma_f32_16x16x32_bf16 v[0:3], v[8:11], v[242:245], v[0:3]
	v_mfma_f32_16x16x32_bf16 v[24:27], v[20:23], v[228:231], v[16:19]
	v_mfma_f32_16x16x32_bf16 v[16:19], v[28:31], v[224:227], v[170:173]
	v_mfma_f32_16x16x32_bf16 v[8:11], v[20:23], v[246:249], v[0:3]
	v_mfma_f32_16x16x32_bf16 v[0:3], v[28:31], v[242:245], v[4:7]
	v_mfma_f32_16x16x32_bf16 v[16:19], v[212:215], v[228:231], v[16:19]
	v_mfma_f32_16x16x32_bf16 v[0:3], v[212:215], v[246:249], v[0:3]
	s_setprio 0
	s_setprio 1
	v_mfma_f32_16x16x32_bf16 v[4:7], v[216:219], v[36:39], v[12:15]
	v_mfma_f32_16x16x32_bf16 v[64:67], v[220:223], v[44:47], v[4:7]
	v_mfma_f32_16x16x32_bf16 v[4:7], v[234:237], v[36:39], v[174:177]
	v_mfma_f32_16x16x32_bf16 v[52:55], v[238:241], v[44:47], v[4:7]
	v_mfma_f32_16x16x32_bf16 v[4:7], v[216:219], v[180:183], v[188:191]
	v_mfma_f32_16x16x32_bf16 v[44:47], v[220:223], v[184:187], v[4:7]
	v_mfma_f32_16x16x32_bf16 v[4:7], v[234:237], v[180:183], v[192:195]
	v_mfma_f32_16x16x32_bf16 v[36:39], v[238:241], v[184:187], v[4:7]
	v_mfma_f32_16x16x32_bf16 v[4:7], v[216:219], v[224:227], v[196:199]
	v_mfma_f32_16x16x32_bf16 v[28:31], v[220:223], v[228:231], v[4:7]
	v_mfma_f32_16x16x32_bf16 v[4:7], v[234:237], v[224:227], v[200:203]
	v_mfma_f32_16x16x32_bf16 v[20:23], v[238:241], v[228:231], v[4:7]
	v_mfma_f32_16x16x32_bf16 v[4:7], v[216:219], v[242:245], v[204:207]
	v_mfma_f32_16x16x32_bf16 v[12:15], v[220:223], v[246:249], v[4:7]
	v_mfma_f32_16x16x32_bf16 v[4:7], v[234:237], v[242:245], v[208:211]
	v_mfma_f32_16x16x32_bf16 v[4:7], v[238:241], v[246:249], v[4:7]
	s_setprio 0
	s_barrier
	s_add_u32 s3, s0, 0x200
	s_addc_u32 s2, s1, 0
	s_add_u32 s0, s34, 0xc04000
	s_addc_u32 s1, s35, 0
	s_mov_b32 s18, 0
.LBB0_478:
	ds_read_b128 v[146:149], v142
	ds_read_b128 v[150:153], v142 offset:1024
	ds_read_b128 v[158:161], v142 offset:2048
	ds_read_b128 v[162:165], v142 offset:3072
	ds_read_b128 v[166:169], v143
	ds_read_b128 v[170:173], v143 offset:1024
	ds_read_b128 v[174:177], v143 offset:2048
	ds_read_b128 v[180:183], v143 offset:3072
	s_add_u32 s10, s0, 0x3fc000
	s_addc_u32 s11, s1, 0
	s_cmp_eq_u32 s18, 12
	s_cselect_b32 s44, s27, s10
	s_cselect_b32 s45, s25, s11
	s_cselect_b32 s42, s58, s3
	s_cselect_b32 s43, s57, s2
	s_add_u32 s34, s44, 0x400000
	s_addc_u32 s35, s45, 0
	s_mov_b32 m0, s59
	v_lshl_add_u64 v[154:155], s[0:1], 0, v[140:141]
	ds_read_b128 v[184:187], v156
	ds_read_b128 v[188:191], v156 offset:1024
	ds_read_b128 v[192:195], v156 offset:2048
	ds_read_b128 v[196:199], v156 offset:3072
	ds_read_b128 v[200:203], v156 offset:4096
	ds_read_b128 v[204:207], v156 offset:5120
	ds_read_b128 v[208:211], v156 offset:6144
	ds_read_b128 v[212:215], v156 offset:7168
	global_load_lds_dwordx4 v[154:155], off
	v_lshl_add_u64 v[154:155], s[0:1], 0, v[138:139]
	s_mov_b32 m0, s60
	s_nop 0
	global_load_lds_dwordx4 v[154:155], off
	s_sleep 3
	s_waitcnt vmcnt(8)
	s_waitcnt lgkmcnt(0)
	s_barrier
	s_setprio 1
	s_waitcnt lgkmcnt(0)
	v_mfma_f32_16x16x32_bf16 v[122:125], v[146:149], v[184:187], v[122:125]
	v_mfma_f32_16x16x32_bf16 v[114:117], v[158:161], v[184:187], v[114:117]
	v_mfma_f32_16x16x32_bf16 v[106:109], v[146:149], v[192:195], v[106:109]
	v_mfma_f32_16x16x32_bf16 v[98:101], v[158:161], v[192:195], v[98:101]
	v_mfma_f32_16x16x32_bf16 v[88:91], v[146:149], v[200:203], v[88:91]
	v_mfma_f32_16x16x32_bf16 v[80:83], v[158:161], v[200:203], v[80:83]
	v_mfma_f32_16x16x32_bf16 v[72:75], v[146:149], v[208:211], v[72:75]
	v_mfma_f32_16x16x32_bf16 v[60:63], v[158:161], v[208:211], v[60:63]
	v_mfma_f32_16x16x32_bf16 v[122:125], v[150:153], v[188:191], v[122:125]
	v_mfma_f32_16x16x32_bf16 v[114:117], v[162:165], v[188:191], v[114:117]
	v_mfma_f32_16x16x32_bf16 v[106:109], v[150:153], v[196:199], v[106:109]
	v_mfma_f32_16x16x32_bf16 v[98:101], v[162:165], v[196:199], v[98:101]
	v_mfma_f32_16x16x32_bf16 v[88:91], v[150:153], v[204:207], v[88:91]
	v_mfma_f32_16x16x32_bf16 v[80:83], v[162:165], v[204:207], v[80:83]
	v_mfma_f32_16x16x32_bf16 v[72:75], v[150:153], v[212:215], v[72:75]
	v_mfma_f32_16x16x32_bf16 v[60:63], v[162:165], v[212:215], v[60:63]
	s_setprio 0
	s_setprio 1
	v_mfma_f32_16x16x32_bf16 v[126:129], v[166:169], v[184:187], v[126:129]
	v_mfma_f32_16x16x32_bf16 v[118:121], v[174:177], v[184:187], v[118:121]
	v_mfma_f32_16x16x32_bf16 v[110:113], v[166:169], v[192:195], v[110:113]
	v_mfma_f32_16x16x32_bf16 v[102:105], v[174:177], v[192:195], v[102:105]
	v_mfma_f32_16x16x32_bf16 v[92:95], v[166:169], v[200:203], v[92:95]
	v_mfma_f32_16x16x32_bf16 v[84:87], v[174:177], v[200:203], v[84:87]
	v_mfma_f32_16x16x32_bf16 v[76:79], v[166:169], v[208:211], v[76:79]
	v_mfma_f32_16x16x32_bf16 v[68:71], v[174:177], v[208:211], v[68:71]
	v_mfma_f32_16x16x32_bf16 v[126:129], v[170:173], v[188:191], v[126:129]
	v_mfma_f32_16x16x32_bf16 v[118:121], v[180:183], v[188:191], v[118:121]
	v_mfma_f32_16x16x32_bf16 v[110:113], v[170:173], v[196:199], v[110:113]
	v_mfma_f32_16x16x32_bf16 v[102:105], v[180:183], v[196:199], v[102:105]
	v_mfma_f32_16x16x32_bf16 v[92:95], v[170:173], v[204:207], v[92:95]
	v_mfma_f32_16x16x32_bf16 v[84:87], v[180:183], v[204:207], v[84:87]
	v_mfma_f32_16x16x32_bf16 v[76:79], v[170:173], v[212:215], v[76:79]
	v_mfma_f32_16x16x32_bf16 v[68:71], v[180:183], v[212:215], v[68:71]
	s_setprio 0
	s_barrier
	s_mov_b32 m0, s61
	v_lshl_add_u64 v[154:155], s[42:43], 0, v[132:133]
	s_add_u32 s10, s42, 0x40000
	ds_read_b128 v[184:187], v156 offset:16384
	ds_read_b128 v[188:191], v156 offset:17408
	ds_read_b128 v[192:195], v156 offset:18432
	ds_read_b128 v[196:199], v156 offset:19456
	ds_read_b128 v[200:203], v156 offset:20480
	ds_read_b128 v[204:207], v156 offset:21504
	ds_read_b128 v[208:211], v156 offset:22528
	ds_read_b128 v[212:215], v156 offset:23552
	global_load_lds_dwordx4 v[154:155], off
	v_lshl_add_u64 v[178:179], s[42:43], 0, v[136:137]
	s_mov_b32 m0, s96
	s_addc_u32 s11, s43, 0
	global_load_lds_dwordx4 v[178:179], off
	v_lshl_add_u64 v[216:217], s[10:11], 0, v[132:133]
	s_mov_b32 m0, s97
	s_nop 0
	global_load_lds_dwordx4 v[216:217], off
	v_lshl_add_u64 v[216:217], s[10:11], 0, v[136:137]
	s_mov_b32 m0, s98
	s_nop 0
	global_load_lds_dwordx4 v[216:217], off
	v_lshl_add_u64 v[216:217], s[44:45], 0, v[130:131]
	s_mov_b32 m0, s23
	s_nop 0
	global_load_lds_dwordx4 v[216:217], off
	v_lshl_add_u64 v[216:217], s[44:45], 0, v[134:135]
	s_mov_b32 m0, s39
	s_nop 0
	global_load_lds_dwordx4 v[216:217], off
	s_sleep 3
	s_waitcnt vmcnt(8)
	s_waitcnt lgkmcnt(0)
	s_barrier
	s_setprio 1
	s_waitcnt lgkmcnt(0)
	v_mfma_f32_16x16x32_bf16 v[56:59], v[146:149], v[184:187], v[56:59]
	v_mfma_f32_16x16x32_bf16 v[48:51], v[158:161], v[184:187], v[48:51]
	v_mfma_f32_16x16x32_bf16 v[40:43], v[146:149], v[192:195], v[40:43]
	v_mfma_f32_16x16x32_bf16 v[32:35], v[158:161], v[192:195], v[32:35]
	v_mfma_f32_16x16x32_bf16 v[24:27], v[146:149], v[200:203], v[24:27]
	v_mfma_f32_16x16x32_bf16 v[16:19], v[158:161], v[200:203], v[16:19]
	v_mfma_f32_16x16x32_bf16 v[8:11], v[146:149], v[208:211], v[8:11]
	v_mfma_f32_16x16x32_bf16 v[0:3], v[158:161], v[208:211], v[0:3]
	v_mfma_f32_16x16x32_bf16 v[56:59], v[150:153], v[188:191], v[56:59]
	v_mfma_f32_16x16x32_bf16 v[48:51], v[162:165], v[188:191], v[48:51]
	v_mfma_f32_16x16x32_bf16 v[40:43], v[150:153], v[196:199], v[40:43]
	v_mfma_f32_16x16x32_bf16 v[32:35], v[162:165], v[196:199], v[32:35]
	v_mfma_f32_16x16x32_bf16 v[24:27], v[150:153], v[204:207], v[24:27]
	v_mfma_f32_16x16x32_bf16 v[16:19], v[162:165], v[204:207], v[16:19]
	v_mfma_f32_16x16x32_bf16 v[8:11], v[150:153], v[212:215], v[8:11]
	v_mfma_f32_16x16x32_bf16 v[0:3], v[162:165], v[212:215], v[0:3]
	s_setprio 0
	s_setprio 1
	v_mfma_f32_16x16x32_bf16 v[64:67], v[166:169], v[184:187], v[64:67]
	v_mfma_f32_16x16x32_bf16 v[52:55], v[174:177], v[184:187], v[52:55]
	v_mfma_f32_16x16x32_bf16 v[44:47], v[166:169], v[192:195], v[44:47]
	v_mfma_f32_16x16x32_bf16 v[36:39], v[174:177], v[192:195], v[36:39]
	v_mfma_f32_16x16x32_bf16 v[28:31], v[166:169], v[200:203], v[28:31]
	v_mfma_f32_16x16x32_bf16 v[20:23], v[174:177], v[200:203], v[20:23]
	v_mfma_f32_16x16x32_bf16 v[12:15], v[166:169], v[208:211], v[12:15]
	v_mfma_f32_16x16x32_bf16 v[4:7], v[174:177], v[208:211], v[4:7]
	v_mfma_f32_16x16x32_bf16 v[64:67], v[170:173], v[188:191], v[64:67]
	v_mfma_f32_16x16x32_bf16 v[52:55], v[180:183], v[188:191], v[52:55]
	v_mfma_f32_16x16x32_bf16 v[44:47], v[170:173], v[196:199], v[44:47]
	v_mfma_f32_16x16x32_bf16 v[36:39], v[180:183], v[196:199], v[36:39]
	v_mfma_f32_16x16x32_bf16 v[28:31], v[170:173], v[204:207], v[28:31]
	v_mfma_f32_16x16x32_bf16 v[20:23], v[180:183], v[204:207], v[20:23]
	v_mfma_f32_16x16x32_bf16 v[12:15], v[170:173], v[212:215], v[12:15]
	v_mfma_f32_16x16x32_bf16 v[4:7], v[180:183], v[212:215], v[4:7]
	s_setprio 0
	s_barrier
	ds_read_b128 v[146:149], v144
	ds_read_b128 v[150:153], v144 offset:1024
	ds_read_b128 v[158:161], v144 offset:2048
	ds_read_b128 v[162:165], v144 offset:3072
	ds_read_b128 v[166:169], v145
	ds_read_b128 v[170:173], v145 offset:1024
	ds_read_b128 v[174:177], v145 offset:2048
	ds_read_b128 v[180:183], v145 offset:3072
	s_add_u32 s10, s44, 0x4000
	s_addc_u32 s11, s45, 0
	s_mov_b32 m0, s46
	v_lshl_add_u64 v[216:217], s[10:11], 0, v[130:131]
	ds_read_b128 v[184:187], v156 offset:32768
	ds_read_b128 v[188:191], v156 offset:33792
	ds_read_b128 v[192:195], v156 offset:34816
	ds_read_b128 v[196:199], v156 offset:35840
	ds_read_b128 v[200:203], v156 offset:36864
	ds_read_b128 v[204:207], v156 offset:37888
	ds_read_b128 v[208:211], v156 offset:38912
	ds_read_b128 v[212:215], v156 offset:39936
	global_load_lds_dwordx4 v[216:217], off
	v_lshl_add_u64 v[216:217], s[10:11], 0, v[134:135]
	s_mov_b32 m0, s47
	s_nop 0
	global_load_lds_dwordx4 v[216:217], off
	s_sleep 3
	s_waitcnt vmcnt(8)
	s_waitcnt lgkmcnt(0)
	s_barrier
	s_setprio 1
	s_waitcnt lgkmcnt(0)
	v_mfma_f32_16x16x32_bf16 v[122:125], v[146:149], v[184:187], v[122:125]
	v_mfma_f32_16x16x32_bf16 v[114:117], v[158:161], v[184:187], v[114:117]
	v_mfma_f32_16x16x32_bf16 v[106:109], v[146:149], v[192:195], v[106:109]
	v_mfma_f32_16x16x32_bf16 v[98:101], v[158:161], v[192:195], v[98:101]
	v_mfma_f32_16x16x32_bf16 v[88:91], v[146:149], v[200:203], v[88:91]
	v_mfma_f32_16x16x32_bf16 v[80:83], v[158:161], v[200:203], v[80:83]
	v_mfma_f32_16x16x32_bf16 v[72:75], v[146:149], v[208:211], v[72:75]
	v_mfma_f32_16x16x32_bf16 v[60:63], v[158:161], v[208:211], v[60:63]
	v_mfma_f32_16x16x32_bf16 v[122:125], v[150:153], v[188:191], v[122:125]
	v_mfma_f32_16x16x32_bf16 v[114:117], v[162:165], v[188:191], v[114:117]
	v_mfma_f32_16x16x32_bf16 v[106:109], v[150:153], v[196:199], v[106:109]
	v_mfma_f32_16x16x32_bf16 v[98:101], v[162:165], v[196:199], v[98:101]
	v_mfma_f32_16x16x32_bf16 v[88:91], v[150:153], v[204:207], v[88:91]
	v_mfma_f32_16x16x32_bf16 v[80:83], v[162:165], v[204:207], v[80:83]
	v_mfma_f32_16x16x32_bf16 v[72:75], v[150:153], v[212:215], v[72:75]
	v_mfma_f32_16x16x32_bf16 v[60:63], v[162:165], v[212:215], v[60:63]
	s_setprio 0
	s_setprio 1
	v_mfma_f32_16x16x32_bf16 v[126:129], v[166:169], v[184:187], v[126:129]
	v_mfma_f32_16x16x32_bf16 v[118:121], v[174:177], v[184:187], v[118:121]
	v_mfma_f32_16x16x32_bf16 v[110:113], v[166:169], v[192:195], v[110:113]
	v_mfma_f32_16x16x32_bf16 v[102:105], v[174:177], v[192:195], v[102:105]
	v_mfma_f32_16x16x32_bf16 v[92:95], v[166:169], v[200:203], v[92:95]
	v_mfma_f32_16x16x32_bf16 v[84:87], v[174:177], v[200:203], v[84:87]
	v_mfma_f32_16x16x32_bf16 v[76:79], v[166:169], v[208:211], v[76:79]
	v_mfma_f32_16x16x32_bf16 v[68:71], v[174:177], v[208:211], v[68:71]
	v_mfma_f32_16x16x32_bf16 v[126:129], v[170:173], v[188:191], v[126:129]
	v_mfma_f32_16x16x32_bf16 v[118:121], v[180:183], v[188:191], v[118:121]
	v_mfma_f32_16x16x32_bf16 v[110:113], v[170:173], v[196:199], v[110:113]
	v_mfma_f32_16x16x32_bf16 v[102:105], v[180:183], v[196:199], v[102:105]
	v_mfma_f32_16x16x32_bf16 v[92:95], v[170:173], v[204:207], v[92:95]
	v_mfma_f32_16x16x32_bf16 v[84:87], v[180:183], v[204:207], v[84:87]
	v_mfma_f32_16x16x32_bf16 v[76:79], v[170:173], v[212:215], v[76:79]
	v_mfma_f32_16x16x32_bf16 v[68:71], v[180:183], v[212:215], v[68:71]
	s_setprio 0
	s_barrier
; template <class Epi, class Sched, bool ALIGN_EPI = false, bool SP2 = false>
; __device__ __forceinline__ void gemm_phase(PG8_LAS unsigned char* lds, const Gemm g, const Sched& S, const Epi& E) {
;     ...
;         if constexpr (Epi::PEEL) {
;             const char* a1 = cA + kstepA; const char* a2 = cA + 2 * kstepA; const char* b2 = cB + 2 * kstepB; const char* a3 = a2 + kstepA; const char* b3 = b2 + kstepB;
;             PG8_ITER(8);
;         }
;         for (int t = (Epi::PEEL ? 2 : 0); t < nt; t += 2) {
;             const bool last = (t == nt - 2);
;             const char* a1 = cA + (size_t)(t + 1) * kstepA;
;             const char* a2 = last ? nA : cA + (size_t)(t + 2) * kstepA; const char* b2 = last ? nB : cB + (size_t)(t + 2) * kstepB;
;             const char* a3 = a2 + kstepA; const char* b3 = b2 + kstepB;
;             PG8_ITER(8);
;         }
	s_mov_b32 m0, s99
	v_lshl_add_u64 v[154:155], v[154:155], 0, s[36:37]
	s_add_u32 s10, s42, 0x40080
	ds_read_b128 v[184:187], v156 offset:49152
	ds_read_b128 v[188:191], v156 offset:50176
	ds_read_b128 v[192:195], v156 offset:51200
	ds_read_b128 v[196:199], v156 offset:52224
	ds_read_b128 v[200:203], v156 offset:53248
	ds_read_b128 v[204:207], v156 offset:54272
	ds_read_b128 v[208:211], v156 offset:55296
	ds_read_b128 v[212:215], v156 offset:56320
	global_load_lds_dwordx4 v[154:155], off
	v_lshl_add_u64 v[154:155], v[178:179], 0, s[36:37]
	s_mov_b32 m0, vcc_lo
	s_addc_u32 s11, s43, 0
	global_load_lds_dwordx4 v[154:155], off
	v_lshl_add_u64 v[154:155], s[10:11], 0, v[132:133]
	s_mov_b32 m0, vcc_hi
	s_nop 0
	global_load_lds_dwordx4 v[154:155], off
	v_lshl_add_u64 v[154:155], s[10:11], 0, v[136:137]
	s_mov_b32 m0, s38
	s_nop 0
	global_load_lds_dwordx4 v[154:155], off
	v_lshl_add_u64 v[154:155], s[34:35], 0, v[130:131]
	s_mov_b32 m0, s49
	s_nop 0
	global_load_lds_dwordx4 v[154:155], off
	v_lshl_add_u64 v[154:155], s[34:35], 0, v[134:135]
	s_mov_b32 m0, s50
	s_nop 0
	global_load_lds_dwordx4 v[154:155], off
	s_sleep 3
	s_waitcnt vmcnt(8)
	s_waitcnt lgkmcnt(0)
	s_barrier
	s_setprio 1
	s_waitcnt lgkmcnt(0)
	v_mfma_f32_16x16x32_bf16 v[56:59], v[146:149], v[184:187], v[56:59]
	v_mfma_f32_16x16x32_bf16 v[48:51], v[158:161], v[184:187], v[48:51]
	v_mfma_f32_16x16x32_bf16 v[40:43], v[146:149], v[192:195], v[40:43]
	v_mfma_f32_16x16x32_bf16 v[32:35], v[158:161], v[192:195], v[32:35]
	v_mfma_f32_16x16x32_bf16 v[24:27], v[146:149], v[200:203], v[24:27]
	v_mfma_f32_16x16x32_bf16 v[16:19], v[158:161], v[200:203], v[16:19]
	v_mfma_f32_16x16x32_bf16 v[8:11], v[146:149], v[208:211], v[8:11]
	v_mfma_f32_16x16x32_bf16 v[0:3], v[158:161], v[208:211], v[0:3]
	v_mfma_f32_16x16x32_bf16 v[56:59], v[150:153], v[188:191], v[56:59]
	v_mfma_f32_16x16x32_bf16 v[48:51], v[162:165], v[188:191], v[48:51]
	v_mfma_f32_16x16x32_bf16 v[40:43], v[150:153], v[196:199], v[40:43]
	v_mfma_f32_16x16x32_bf16 v[32:35], v[162:165], v[196:199], v[32:35]
	v_mfma_f32_16x16x32_bf16 v[24:27], v[150:153], v[204:207], v[24:27]
	v_mfma_f32_16x16x32_bf16 v[16:19], v[162:165], v[204:207], v[16:19]
	v_mfma_f32_16x16x32_bf16 v[8:11], v[150:153], v[212:215], v[8:11]
	v_mfma_f32_16x16x32_bf16 v[0:3], v[162:165], v[212:215], v[0:3]
	s_setprio 0
	s_setprio 1
	v_mfma_f32_16x16x32_bf16 v[64:67], v[166:169], v[184:187], v[64:67]
	v_mfma_f32_16x16x32_bf16 v[52:55], v[174:177], v[184:187], v[52:55]
	v_mfma_f32_16x16x32_bf16 v[44:47], v[166:169], v[192:195], v[44:47]
	v_mfma_f32_16x16x32_bf16 v[36:39], v[174:177], v[192:195], v[36:39]
	v_mfma_f32_16x16x32_bf16 v[28:31], v[166:169], v[200:203], v[28:31]
	v_mfma_f32_16x16x32_bf16 v[20:23], v[174:177], v[200:203], v[20:23]
	v_mfma_f32_16x16x32_bf16 v[12:15], v[166:169], v[208:211], v[12:15]
	v_mfma_f32_16x16x32_bf16 v[4:7], v[174:177], v[208:211], v[4:7]
	v_mfma_f32_16x16x32_bf16 v[64:67], v[170:173], v[188:191], v[64:67]
	v_mfma_f32_16x16x32_bf16 v[52:55], v[180:183], v[188:191], v[52:55]
	v_mfma_f32_16x16x32_bf16 v[44:47], v[170:173], v[196:199], v[44:47]
	v_mfma_f32_16x16x32_bf16 v[36:39], v[180:183], v[196:199], v[36:39]
	v_mfma_f32_16x16x32_bf16 v[28:31], v[170:173], v[204:207], v[28:31]
	v_mfma_f32_16x16x32_bf16 v[20:23], v[180:183], v[204:207], v[20:23]
	v_mfma_f32_16x16x32_bf16 v[12:15], v[170:173], v[212:215], v[12:15]
	v_mfma_f32_16x16x32_bf16 v[4:7], v[180:183], v[212:215], v[4:7]
	s_setprio 0
	s_barrier
	s_add_i32 s18, s18, 2
	s_add_u32 s3, s3, 0x100
	s_addc_u32 s2, s2, 0
	s_add_u32 s0, s0, 0x800000
	s_addc_u32 s1, s1, 0
	s_cmp_gt_u32 s18, 13
	s_cbranch_scc0 .LBB0_478
	s_and_b64 vcc, exec, s[16:17]
	s_cbranch_vccz .LBB0_481
	s_barrier
